# FFN row panels relabelled per XCD (16*xcd+8*half+r) so P3->P4 hand-off is XCD-local too; P3->P4 barrier XCD-local (L1 invalidate kept, no L2 writeback, no cross-XCD stage). Each XCD now runs P1..P5 fo
# speedup vs baseline: 1.0242x; 1.0123x over previous
; __device__ __forceinline__ unsigned xb_add(unsigned* p, unsigned v) { return __hip_atomic_fetch_add(p, v, __ATOMIC_RELAXED, __HIP_MEMORY_SCOPE_AGENT); }
; __device__ __forceinline__ void xcd_barrier(const XcdBarrier& b) {
;     ...
;         if (old + 1u == (gen + 1u) * nloc) {
;             __builtin_amdgcn_fence(__ATOMIC_RELEASE, "agent");
;             asm volatile("s_waitcnt vmcnt(0)" ::: "memory");
;             const unsigned og = xb_add(&bar[XB_TOP], 1u);
;             const unsigned tg = og / nx;
;             if (og + 1u == (tg + 1u) * nx) xb_add(&bar[XB_TOPGEN], 1u);
.LBB0_675:
	s_andn2_saveexec_b64 s[8:9], s[8:9]
	s_cbranch_execz .LBB0_695
	s_mov_b64 s[10:11], exec
	s_cmp_eq_u32 s32, 0
	s_cbranch_scc1 .Lxb3_rel
	buffer_wbl2 sc1
	s_waitcnt lgkmcnt(0)
	s_waitcnt vmcnt(0)
	v_mbcnt_lo_u32_b32 v2, s10, 0
	v_mbcnt_hi_u32_b32 v2, s11, v2
	v_cmp_eq_u32_e32 vcc, 0, v2
	s_and_saveexec_b64 s[12:13], vcc
	s_cbranch_execz .LBB0_678
	s_bcnt1_i32_b64 s10, s[10:11]
	v_mov_b32_e32 v3, 0x3000
	v_mov_b32_e32 v4, s10
	global_atomic_add v3, v3, v4, s[84:85] offset:1024 sc0

; __device__ __forceinline__ unsigned xb_add(unsigned* p, unsigned v) { return __hip_atomic_fetch_add(p, v, __ATOMIC_RELAXED, __HIP_MEMORY_SCOPE_AGENT); }
; __device__ __forceinline__ void xcd_barrier(const XcdBarrier& b) {
;     ...
;             __builtin_amdgcn_fence(__ATOMIC_ACQUIRE, "agent");
;             xb_add(&bar[XB_XGEN(b.x)], 1u);
;             asm volatile("s_waitcnt vmcnt(0)" ::: "memory");
.Lxb3_rel:
.LBB0_692:
	s_or_b64 exec, exec, s[10:11]
	s_mov_b64 s[10:11], exec
	v_mbcnt_lo_u32_b32 v1, s10, 0
	v_mbcnt_hi_u32_b32 v1, s11, v1
	v_cmp_eq_u32_e32 vcc, 0, v1
	s_waitcnt vmcnt(0)
	buffer_inv sc1
	s_and_saveexec_b64 s[12:13], vcc
	s_cbranch_execz .LBB0_694
	s_bcnt1_i32_b64 s10, s[10:11]
	v_mov_b32_e32 v1, 0x2000
	v_mov_b32_e32 v2, s10
	global_atomic_add v1, v2, s[6:7] offset:1024

; #define PG8_WAIT_V(n) asm volatile("s_waitcnt vmcnt(" #n ")" ::: "memory")
; #define PG8_BAR __builtin_amdgcn_s_barrier()
; template <class Epi, class Sched>
; __device__ __forceinline__ void gemm_phase(LAS unsigned char* lds, const Gemm g, const Sched& S, const Epi& E) {
;     int tid_ = threadIdx.x; asm volatile("" : "+v"(tid_));
;     const int tid = tid_, wid = __builtin_amdgcn_readfirstlane(tid >> 6), lane = tid & 63, wr = wid >> 2, wc = wid & 3, fr = lane & 15, fq = lane >> 4;
;     const int K = g.K, nt = K / BK;
;     unsigned voffA[2], voffB[2];
; #pragma unroll
;     for (int i = 0; i < 2; ++i) { int R, C; stage_rc(tid * 16 + i * 8192, R, C);
;         const int Ra = 128 * (R >> 6) + (R & 63);
;         const int Rb = Epi::HEADPERM ? (64 * (R >> 5) + perm32(R & 31)) : ((R & ~31) + perm32(R & 31));
;         voffA[i] = (unsigned)(Ra * g.lda + C) * 2u; voffB[i] = (unsigned)(Rb * K + C) * 2u; }
;     ...
;     const char* cA = (const char*)g.A + (size_t)cur.pm * tstep; const char* cB = (const char*)g.Bt + (size_t)cur.pn * tstep;
;     PG8_STAGE(PG8_SB(0, 0), cB, voffB); PG8_STAGE(PG8_SB(0, 1), cB + hstepB, voffB); PG8_STAGE(PG8_SA(0, 0), cA, voffA); PG8_STAGE(PG8_SA(0, 1), cA + hstepA, voffA);
;     if (wr == 1) PG8_BAR;
;     PG8_WAIT_V(2); PG8_BAR;
;     PG8_STAGE(PG8_SB(1, 0), cB + kstep, voffB); PG8_STAGE(PG8_SA(1, 0), cA + kstepA, voffA); PG8_STAGE(PG8_SB(1, 1), cB + hstepB + kstep, voffB);
.LBB0_699:
	v_readlane_b32 s0, v243, 4
	v_mov_b32_e32 v2, v0
	v_readlane_b32 s1, v243, 5
	s_andn2_b64 vcc, exec, s[0:1]
	v_readfirstlane_b32 s1, v2
	s_cbranch_vccnz .LBB0_719
	v_mov_b32_e32 v240, 0x3800
	global_load_dword v241, v240, s[84:85] sc1
	s_waitcnt vmcnt(0)
	v_readfirstlane_b32 s32, v241
	s_mov_b32 s100, -1
	v_bfe_i32 v5, v2, 27, 1
	v_lshlrev_b32_e32 v3, 4, v2
	v_lshrrev_b32_e32 v5, 22, v5
	v_add_u32_e32 v5, v3, v5
	v_and_b32_e32 v5, 0xfffffc00, v5
	v_sub_u32_e32 v5, v3, v5
	v_ashrrev_i32_e32 v4, 31, v2
	v_lshrrev_b32_e32 v6, 4, v5
	v_lshrrev_b32_e32 v4, 26, v4
	v_bitop3_b32 v5, v6, v5, 32 bitop3:0x6c
	v_add_u32_e32 v4, v2, v4
	v_ashrrev_i32_e32 v7, 31, v5
	v_ashrrev_i32_e32 v4, 6, v4
	v_lshrrev_b32_e32 v7, 26, v7
	v_lshlrev_b32_e32 v6, 3, v4
	v_add_u32_e32 v7, v5, v7
	v_and_b32_e32 v6, -16, v6
	v_ashrrev_i32_e32 v8, 6, v7
	v_and_b32_e32 v7, 0xc0, v7
	v_add_u32_e32 v6, v8, v6
	v_sub_u32_e32 v5, v5, v7
	v_lshlrev_b32_e32 v4, 5, v4
	v_ashrrev_i16_sdwa v5, v164, sext(v5) dst_sel:DWORD dst_unused:UNUSED_PAD src0_sel:DWORD src1_sel:BYTE_0
	v_lshlrev_b32_e32 v7, 1, v6
	v_and_b32_e32 v9, 63, v6
	s_mov_b32 s4, 0x1fff80
	v_lshrrev_b32_e32 v10, 2, v6
	v_and_b32_e32 v8, 3, v8
	s_mov_b32 s5, 0x1fffe0
	v_and_b32_e32 v4, 32, v4
	v_bfe_i32 v5, v5, 0, 16
	v_and_or_b32 v9, v7, s4, v9
	v_and_b32_e32 v7, 24, v7
	v_and_b32_e32 v10, 4, v10
	v_and_or_b32 v6, v6, s5, v8
	v_or3_b32 v6, v6, v10, v7
	v_add_lshl_u32 v4, v4, v5, 1
	v_add_u32_e32 v3, 0x2000, v3
	v_lshl_add_u32 v165, v9, 11, v4
	v_lshl_add_u32 v166, v6, 11, v4
	v_ashrrev_i32_e32 v4, 31, v3
	v_lshrrev_b32_e32 v4, 22, v4
	v_add_u32_e32 v4, v3, v4
	v_ashrrev_i32_e32 v4, 10, v4
	v_mul_i32_i24_e32 v5, 0x400, v4
	v_sub_u32_e32 v3, v3, v5
	v_lshrrev_b32_e32 v5, 4, v3
	v_bitop3_b32 v3, v5, v3, 32 bitop3:0x6c
	v_ashrrev_i32_e32 v6, 31, v3
	v_lshrrev_b32_e32 v6, 26, v6
	v_lshlrev_b32_e32 v5, 3, v4
	v_add_u32_e32 v6, v3, v6
	v_and_b32_e32 v5, -16, v5
	v_ashrrev_i32_e32 v7, 6, v6
	v_and_b32_e32 v6, 0xc0, v6
	s_ashr_i32 s0, s1, 6
	v_add_u32_e32 v5, v7, v5
	v_sub_u32_e32 v3, v3, v6
	v_and_b32_e32 v7, 3, v7
	v_lshlrev_b32_e32 v4, 5, v4
	v_ashrrev_i16_sdwa v3, v164, sext(v3) dst_sel:DWORD dst_unused:UNUSED_PAD src0_sel:DWORD src1_sel:BYTE_0
	v_lshlrev_b32_e32 v6, 1, v5
	v_and_b32_e32 v8, 63, v5
	v_lshrrev_b32_e32 v9, 2, v5
	v_and_or_b32 v5, v5, s5, v7
	s_lshl_b32 s5, s0, 10
	v_and_b32_e32 v4, 32, v4
	v_bfe_i32 v3, v3, 0, 16
	v_and_or_b32 v8, v6, s4, v8
	v_and_b32_e32 v6, 24, v6
	v_and_b32_e32 v9, 4, v9
	v_readlane_b32 s6, v243, 28
	s_add_i32 s35, s5, 0
	v_or3_b32 v5, v5, v9, v6
	v_add_lshl_u32 v3, v4, v3, 1
	s_and_b32 s7, s6, -8
	s_add_i32 s10, s6, s7
	s_lshr_b32 s7, s34, 3
	s_add_i32 s10, s10, s7
	s_add_i32 s64, s35, 0x10000
	s_mov_b32 m0, s64
	s_nop 0
	global_load_lds_dwordx4 v166, s[70:71]
	v_lshl_add_u32 v168, v5, 11, v3
	s_ashr_i32 s11, s10, 31
	s_add_i32 s65, s35, 0x12000
	s_mov_b32 m0, s65
	s_nop 0
	global_load_lds_dwordx4 v168, s[70:71]
	v_readlane_b32 s8, v243, 24
	s_ashr_i32 s4, s1, 8
	s_lshl_b64 s[6:7], s[10:11], 19
	s_add_i32 s38, s35, 0x14000
	v_readlane_b32 s9, v243, 25
	s_mov_b32 m0, s38
	s_nop 0
	global_load_lds_dwordx4 v166, s[8:9]
	s_add_i32 s39, s35, 0x16000
	s_mov_b32 m0, s39
	s_nop 0
	global_load_lds_dwordx4 v168, s[8:9]
	s_add_u32 s6, s42, s6
	s_addc_u32 s7, s43, s7
	s_mov_b32 m0, s35
	s_nop 0
	global_load_lds_dwordx4 v165, s[6:7]
	s_add_i32 s48, s35, 0x2000
	s_add_i32 s49, s35, 0x4000
	v_lshl_add_u32 v167, v8, 11, v3
	s_mov_b32 m0, s48
	s_nop 0
	global_load_lds_dwordx4 v167, s[6:7]
	s_add_u32 s8, s6, 0x20000
	s_addc_u32 s9, s7, 0
	s_mov_b32 m0, s49
	s_nop 0
	global_load_lds_dwordx4 v165, s[8:9]
	s_add_i32 s25, s35, 0x6000
	s_mov_b32 m0, s25
	s_nop 0
	global_load_lds_dwordx4 v167, s[8:9]
	s_cmp_eq_u32 s4, 1
	s_cselect_b64 s[96:97], -1, 0
	s_cmp_lg_u32 s4, 1
	s_cbranch_scc1 .LBB0_702
	s_barrier

;     __device__ bool next(int i, Unit& u) const {
;         const long L = (long)i * G + c; if (L >= (long)nwg * rep) return false;
;         int wgid = (int)(L % nwg); { const int q = nwg / NXCD, r = nwg % NXCD, xcd = wgid % NXCD, off = wgid / NXCD; wgid = (xcd < r ? xcd * (q + 1) : r * (q + 1) + (xcd - r) * q) + off; }
;         const int nig = WGM * nN, gid = wgid / nig, fm = gid * WGM, gsz = (nM - fm) < WGM ? (nM - fm) : WGM;
;         u.pm = pm0 + fm + ((wgid % nig) % gsz); u.pn = (wgid % nig) / gsz; return true;
.LBB0_710:
	s_sext_i32_i16 s0, s4
	s_lshr_b32 s0, s0, 3
	s_add_i32 s0, s5, s0
	s_sext_i32_i16 s1, s0
	s_bfe_u32 s1, s1, 0x70018
	s_add_i32 s1, s0, s1
	s_sext_i32_i16 s4, s1
	s_and_b32 s1, s1, 0xff80
	s_sub_i32 s0, s0, s1
	s_bfe_i32 s1, s0, 0x80000
	s_bfe_u32 s1, s1, 0x3000c
	s_add_i32 s1, s0, s1
	s_ashr_i32 s4, s4, 7
	s_bfe_i32 s5, s1, 0x80000
	s_and_b32 s1, s1, 0xf8
	s_lshl_b32 s4, s4, 4
	s_sub_i32 s0, s0, s1
	s_lshr_b32 s1, s34, 3
	s_add_i32 s4, s4, s1
	s_sext_i32_i16 s5, s5
	s_sext_i32_i8 s0, s0
	s_add_i32 s0, s4, s0
	s_ashr_i32 s4, s5, 3

; #define PG8_WAIT_V(n) asm volatile("s_waitcnt vmcnt(" #n ")" ::: "memory")
; #define PG8_BAR __builtin_amdgcn_s_barrier()
; template <class Epi, class Sched>
; __device__ __forceinline__ void gemm_phase(LAS unsigned char* lds, const Gemm g, const Sched& S, const Epi& E) {
;     int tid_ = threadIdx.x; asm volatile("" : "+v"(tid_));
;     const int tid = tid_, wid = __builtin_amdgcn_readfirstlane(tid >> 6), lane = tid & 63, wr = wid >> 2, wc = wid & 3, fr = lane & 15, fq = lane >> 4;
;     const int K = g.K, nt = K / BK;
;     unsigned voffA[2], voffB[2];
; #pragma unroll
;     for (int i = 0; i < 2; ++i) { int R, C; stage_rc(tid * 16 + i * 8192, R, C);
;         const int Ra = 128 * (R >> 6) + (R & 63);
;         const int Rb = Epi::HEADPERM ? (64 * (R >> 5) + perm32(R & 31)) : ((R & ~31) + perm32(R & 31));
;         voffA[i] = (unsigned)(Ra * g.lda + C) * 2u; voffB[i] = (unsigned)(Rb * K + C) * 2u; }
;     ...
;     const char* cA = (const char*)g.A + (size_t)cur.pm * tstep; const char* cB = (const char*)g.Bt + (size_t)cur.pn * tstep;
;     PG8_STAGE(PG8_SB(0, 0), cB, voffB); PG8_STAGE(PG8_SB(0, 1), cB + hstepB, voffB); PG8_STAGE(PG8_SA(0, 0), cA, voffA); PG8_STAGE(PG8_SA(0, 1), cA + hstepA, voffA);
;     if (wr == 1) PG8_BAR;
;     PG8_WAIT_V(2); PG8_BAR;
;     PG8_STAGE(PG8_SB(1, 0), cB + kstep, voffB); PG8_STAGE(PG8_SA(1, 0), cA + kstepA, voffA); PG8_STAGE(PG8_SB(1, 1), cB + hstepB + kstep, voffB);
.LBB0_767:
	s_or_b64 exec, exec, s[0:1]
	v_readlane_b32 s4, v243, 22
	s_waitcnt lgkmcnt(0)
	v_mov_b32_e32 v2, v0
	v_readlane_b32 s5, v243, 23
	s_xor_b64 s[0:1], s[94:95], -1
	s_barrier
	s_andn2_b64 vcc, exec, s[4:5]
	v_readfirstlane_b32 s6, v2
	s_cbranch_vccnz .LBB0_698
	v_bfe_i32 v5, v2, 27, 1
	v_lshlrev_b32_e32 v3, 4, v2
	v_lshrrev_b32_e32 v5, 22, v5
	v_add_u32_e32 v5, v3, v5
	v_and_b32_e32 v5, 0xfffffc00, v5
	v_sub_u32_e32 v5, v3, v5
	v_ashrrev_i32_e32 v4, 31, v2
	v_lshrrev_b32_e32 v6, 4, v5
	v_lshrrev_b32_e32 v4, 26, v4
	v_bitop3_b32 v5, v6, v5, 32 bitop3:0x6c
	v_add_u32_e32 v4, v2, v4
	v_ashrrev_i32_e32 v7, 31, v5
	v_ashrrev_i32_e32 v4, 6, v4
	v_lshrrev_b32_e32 v7, 26, v7
	v_lshlrev_b32_e32 v6, 3, v4
	v_add_u32_e32 v7, v5, v7
	v_and_b32_e32 v6, -16, v6
	v_ashrrev_i32_e32 v8, 6, v7
	v_and_b32_e32 v7, 0xc0, v7
	v_add_u32_e32 v6, v8, v6
	v_sub_u32_e32 v5, v5, v7
	v_lshlrev_b32_e32 v4, 5, v4
	v_ashrrev_i16_sdwa v5, v164, sext(v5) dst_sel:DWORD dst_unused:UNUSED_PAD src0_sel:DWORD src1_sel:BYTE_0
	v_lshlrev_b32_e32 v7, 1, v6
	v_and_b32_e32 v9, 63, v6
	s_mov_b32 s4, 0x1ffff80
	v_lshrrev_b32_e32 v10, 2, v6
	v_and_b32_e32 v8, 3, v8
	s_mov_b32 s5, 0x7ffe0
	v_and_b32_e32 v4, 32, v4
	v_bfe_i32 v5, v5, 0, 16
	v_and_or_b32 v9, v7, s4, v9
	v_and_b32_e32 v7, 24, v7
	v_and_b32_e32 v10, 4, v10
	v_and_or_b32 v6, v6, s5, v8
	v_or3_b32 v6, v6, v10, v7
	v_add_lshl_u32 v4, v4, v5, 1
	v_add_u32_e32 v3, 0x2000, v3
	v_lshl_add_u32 v148, v9, 7, v4
	v_lshl_add_u32 v149, v6, 13, v4
	v_ashrrev_i32_e32 v4, 31, v3
	v_lshrrev_b32_e32 v4, 22, v4
	v_add_u32_e32 v4, v3, v4
	v_ashrrev_i32_e32 v4, 10, v4
	v_mul_i32_i24_e32 v5, 0x400, v4
	v_sub_u32_e32 v3, v3, v5
	v_lshrrev_b32_e32 v5, 4, v3
	v_bitop3_b32 v3, v5, v3, 32 bitop3:0x6c
	v_ashrrev_i32_e32 v6, 31, v3
	v_lshrrev_b32_e32 v6, 26, v6
	v_lshlrev_b32_e32 v5, 3, v4
	v_add_u32_e32 v6, v3, v6
	v_and_b32_e32 v5, -16, v5
	v_ashrrev_i32_e32 v7, 6, v6
	v_and_b32_e32 v6, 0xc0, v6
	v_add_u32_e32 v5, v7, v5
	v_sub_u32_e32 v3, v3, v6
	s_ashr_i32 s7, s6, 6
	v_lshlrev_b32_e32 v4, 5, v4
	v_ashrrev_i16_sdwa v3, v164, sext(v3) dst_sel:DWORD dst_unused:UNUSED_PAD src0_sel:DWORD src1_sel:BYTE_0
	v_lshlrev_b32_e32 v6, 1, v5
	v_and_b32_e32 v8, 63, v5
	v_lshrrev_b32_e32 v9, 2, v5
	v_and_b32_e32 v7, 3, v7
	s_lshl_b32 s9, s7, 10
	v_and_b32_e32 v4, 32, v4
	v_bfe_i32 v3, v3, 0, 16
	v_and_or_b32 v8, v6, s4, v8
	v_and_b32_e32 v6, 24, v6
	v_and_b32_e32 v9, 4, v9
	v_and_or_b32 v5, v5, s5, v7
	v_readlane_b32 s4, v242, 3
	s_add_i32 s21, s9, 0
	v_or3_b32 v5, v5, v9, v6
	v_add_lshl_u32 v3, v4, v3, 1
	s_and_b32 s5, s4, -8
	s_add_i32 s96, s4, s5
	s_lshr_b32 s5, s34, 3
	s_add_i32 s96, s96, s5
	s_add_i32 s22, s21, 0x10000
	s_mov_b32 m0, s22
	s_nop 0
	global_load_lds_dwordx4 v149, s[78:79]
	v_lshl_add_u32 v151, v5, 13, v3
	s_ashr_i32 s97, s96, 31
	s_add_i32 s23, s21, 0x12000
	s_mov_b32 m0, s23
	s_nop 0
	global_load_lds_dwordx4 v151, s[78:79]
	s_ashr_i32 s8, s6, 8
	s_lshl_b64 s[4:5], s[96:97], 21
	s_add_i32 s24, s21, 0x14000
	s_mov_b32 m0, s24
	s_nop 0
	global_load_lds_dwordx4 v149, s[80:81]
	s_add_i32 s25, s21, 0x16000
	s_mov_b32 m0, s25
	s_nop 0
	global_load_lds_dwordx4 v151, s[80:81]
	s_add_u32 s12, s46, s4
	s_addc_u32 s13, s47, s5
	s_mov_b32 m0, s21
	s_nop 0
	global_load_lds_dwordx4 v148, s[12:13]
	v_lshl_add_u32 v150, v8, 7, v3
	s_add_i32 s26, s21, 0x2000
	s_mov_b32 m0, s26
	s_nop 0
	global_load_lds_dwordx4 v150, s[12:13]
	s_add_i32 s28, s21, 0x4000
	s_add_u32 s4, s12, 0x2000
	s_addc_u32 s5, s13, 0
	s_mov_b32 m0, s28
	s_nop 0
	global_load_lds_dwordx4 v148, s[4:5]
	s_add_i32 s30, s21, 0x6000
	s_mov_b32 m0, s30
	s_nop 0
	global_load_lds_dwordx4 v150, s[4:5]
	s_cmp_eq_u32 s8, 1
	s_cselect_b64 s[4:5], -1, 0
	s_cmp_lg_u32 s8, 1
	s_cbranch_scc1 .LBB0_770
	s_barrier

;     __device__ bool next(int i, Unit& u) const {
;         const long L = (long)i * G + c; if (L >= (long)nwg * rep) return false;
;         int wgid = (int)(L % nwg); { const int q = nwg / NXCD, r = nwg % NXCD, xcd = wgid % NXCD, off = wgid / NXCD; wgid = (xcd < r ? xcd * (q + 1) : r * (q + 1) + (xcd - r) * q) + off; }
;         const int nig = WGM * nN, gid = wgid / nig, fm = gid * WGM, gsz = (nM - fm) < WGM ? (nM - fm) : WGM;
;         u.pm = pm0 + fm + ((wgid % nig) % gsz); u.pn = (wgid % nig) / gsz; return true;
.LBB0_778:
	s_sext_i32_i16 s8, s10
	s_lshr_b32 s8, s8, 3
	s_add_i32 s8, s11, s8
	s_sext_i32_i16 s9, s8
	s_bfe_u32 s9, s9, 0x5001a
	s_add_i32 s9, s8, s9
	s_sext_i32_i16 s10, s9
	s_and_b32 s9, s9, 0xffe0
	s_sub_i32 s8, s8, s9
	s_bfe_i32 s9, s8, 0x80000
	s_bfe_u32 s9, s9, 0x3000c
	s_add_i32 s9, s8, s9
	s_ashr_i32 s10, s10, 5
	s_bfe_i32 s11, s9, 0x80000
	s_and_b32 s9, s9, 0xf8
	s_lshl_b32 s10, s10, 4
	s_sub_i32 s8, s8, s9
	s_lshr_b32 s9, s34, 3
	s_add_i32 s10, s10, s9
	s_sext_i32_i16 s11, s11
	s_sext_i32_i8 s8, s8
	s_add_i32 s8, s10, s8
	s_ashr_i32 s10, s11, 3
